# fp16 GEMM units: per-lane staging offsets computed once per phase and kept in free VGPRs; later units redo only two multiply-adds
# baseline (speedup 1.0000x reference)
; #define PG8_ROWS(RA, RB, C2) unsigned RA, RB, C2; { int R0_, C0_; stage_rc((wid * 64 + lane_now()) * 16, R0_, C0_); RA = (unsigned)R0_; RB = (unsigned)((R0_ & ~31) + perm32(R0_ & 31)); C2 = (unsigned)C0_ * 2u; }
; template <bool F8 = false, class Sched, class Epi>
; __device__ __forceinline__ void gemm_phase(LAS unsigned char* lds, const Sched& S, const Epi& E) {
;     ...
;         const bool has_next = S.next(ui + 1, nxt);
;         const char* nA = has_next ? nxt.A : cA; const char* nB = has_next ? nxt.B : cB;
;         const unsigned nK2 = has_next ? (unsigned)nxt.K * 2u : cK2;
;         unsigned nvA, nvB; { PG8_ROWS(ra, rb, c2) nvA = ra * nK2 + c2; nvB = rb * nK2 + c2; }
;         const size_t nh64 = (size_t)64 * nK2, nhs = (size_t)128 * nK2, nbhs = has_next ? nxt.bhs : cbhs;
.LBB0_212:
	s_cmp_lg_u32 s75, 0
	s_cbranch_scc1 .Lrows_fast
	v_mbcnt_lo_u32_b32 v32, -1, 0
	v_mbcnt_hi_u32_b32 v32, -1, v32
	s_cmp_lg_u32 s27, 8
	v_add_u32_e32 v32, s94, v32
	v_ashrrev_i32_e32 v35, 31, v32
	v_lshrrev_b32_e32 v35, 26, v35
	v_lshlrev_b32_e32 v34, 4, v32
	v_add_u32_e32 v35, v32, v35
	v_bfe_i32 v32, v32, 27, 1
	v_lshrrev_b32_e32 v32, 22, v32
	v_add_u32_e32 v32, v34, v32
	v_and_b32_e32 v32, 0xfffffc00, v32
	v_sub_u32_e32 v32, v34, v32
	v_lshrrev_b32_e32 v34, 4, v32
	v_bitop3_b32 v32, v34, v32, 32 bitop3:0x6c
	s_cselect_b64 s[2:3], -1, 0
	s_ashr_i32 s25, s24, 31
	v_ashrrev_i32_e32 v132, 31, v32
	s_and_b64 s[2:3], s[30:31], s[2:3]
	s_lshl_b64 s[6:7], s[24:25], 8
	v_ashrrev_i32_e32 v35, 6, v35
	v_lshrrev_b32_e32 v132, 26, v132
	s_and_b64 s[2:3], s[2:3], exec
	v_lshlrev_b32_e32 v34, 3, v35
	v_add_u32_e32 v132, v32, v132
	s_cselect_b32 s3, s7, s19
	s_cselect_b32 s2, s6, s18
	s_lshl_b32 s25, s24, 1
	v_and_b32_e32 v34, -16, v34
	v_ashrrev_i32_e32 v133, 6, v132
	v_and_b32_e32 v132, 0xc0, v132
	s_and_b64 s[6:7], s[30:31], exec
	v_add_u32_e32 v34, v133, v34
	v_sub_u32_e32 v32, v32, v132
	v_lshlrev_b32_e32 v35, 5, v35
	v_ashrrev_i16_sdwa v32, v222, sext(v32) dst_sel:DWORD dst_unused:UNUSED_PAD src0_sel:DWORD src1_sel:BYTE_0
	v_lshlrev_b32_e32 v132, 1, v34
	v_lshrrev_b32_e32 v134, 2, v34
	v_and_b32_e32 v133, 3, v133
	s_movk_i32 s6, 0xffe0
	s_cselect_b32 s96, s25, s50
	v_and_b32_e32 v35, 32, v35
	v_bfe_i32 v32, v32, 0, 16
	v_and_b32_e32 v132, 24, v132
	v_and_b32_e32 v134, 4, v134
	v_and_or_b32 v133, v34, s6, v133
	v_or3_b32 v132, v133, v134, v132
	v_add_lshl_u32 v32, v35, v32, 1
	s_lshl_b64 s[16:17], s[96:97], 6
	s_lshl_b64 s[18:19], s[96:97], 7
	s_mov_b64 s[52:53], s[78:79]
	s_mov_b32 s54, s45
	v_mov_b32_e32 v196, v34
	v_mov_b32_e32 v197, v132
	v_mov_b32_e32 v242, v32
	v_mov_b32_e32 v243, 0
	v_mad_u64_u32 v[34:35], s[6:7], v34, s96, v[32:33]
	v_mad_u64_u32 v[188:189], s[6:7], v132, s96, v[32:33]
	s_branch .Lrows_join
.Lrows_fast:
	s_cmp_lg_u32 s27, 8
	s_cselect_b64 s[2:3], -1, 0
	s_ashr_i32 s25, s24, 31
	s_and_b64 s[2:3], s[30:31], s[2:3]
	s_lshl_b64 s[6:7], s[24:25], 8
	s_and_b64 s[2:3], s[2:3], exec
	s_cselect_b32 s3, s7, s19
	s_cselect_b32 s2, s6, s18
	s_lshl_b32 s25, s24, 1
	s_and_b64 s[6:7], s[30:31], exec
	s_movk_i32 s6, 0xffe0
	s_cselect_b32 s96, s25, s50
	s_lshl_b64 s[16:17], s[96:97], 6
	s_lshl_b64 s[18:19], s[96:97], 7
	s_mov_b64 s[52:53], s[78:79]
	s_mov_b32 s54, s45
	v_mad_u64_u32 v[34:35], s[6:7], v196, s96, v[242:243]
	v_mad_u64_u32 v[188:189], s[6:7], v197, s96, v[242:243]
.Lrows_join:
	s_cmpk_lt_u32 s50, 0x80
	s_cbranch_scc1 .LBB0_217
	s_and_b64 s[6:7], s[30:31], exec
	s_cselect_b32 s29, s23, s15
	s_cselect_b32 s96, s22, s14
	s_cselect_b32 s73, s21, s43
	s_cselect_b32 s72, s20, s42
	s_cselect_b32 s81, s3, s67
	s_cselect_b32 s80, s2, s66
	s_lshr_b32 s36, s50, 7
	s_add_i32 s68, s36, -2
	s_add_u32 s69, s42, 0x100
	s_addc_u32 s78, s43, 0
	s_add_u32 s8, s14, 0x80
	s_addc_u32 s9, s15, 0
	s_add_u32 s6, s8, s90
	v_mov_b32_e32 v185, v33
	s_addc_u32 s7, s9, s91
	v_lshl_add_u64 v[132:133], s[6:7], 0, v[184:185]
	s_add_u32 s6, s88, s90
	s_addc_u32 s7, s89, s91
	s_add_u32 s6, s8, s6
	s_addc_u32 s7, s9, s7
	v_mov_b32_e32 v35, v33
	v_lshl_add_u64 v[134:135], s[6:7], 0, v[184:185]
	s_mov_b32 s79, 0
	s_mov_b64 s[10:11], 0
	s_branch .LBB0_215
